# XB5: XB4 + second-to-last workgroup of each XCD starts an early L2 write-back
# speedup vs baseline: 1.0104x; 1.0015x over previous
; __device__ __forceinline__ unsigned xb_ld(unsigned* p)              { return __hip_atomic_load(p, __ATOMIC_RELAXED, __HIP_MEMORY_SCOPE_AGENT); }
; __device__ __forceinline__ unsigned xb_add(unsigned* p, unsigned v) { return __hip_atomic_fetch_add(p, v, __ATOMIC_RELAXED, __HIP_MEMORY_SCOPE_AGENT); }
; #define XB_SPIN(cond, bar) do { unsigned _sp = 0; while (cond) { __builtin_amdgcn_s_sleep(1); \
;     if ((++_sp & 255u) == 0u) { if (xb_ld(&(bar)[XB_TMO])) break; if (_sp > XB_SPIN_CAP) { atomicAdd(&(bar)[XB_TMO], 1u); break; } } } } while (0)
; __device__ __forceinline__ void xcd_barrier(const XcdBarrier& b) {
;     ...
;         const unsigned old = xb_add(&bar[XB_XSUB(b.x)], 1u);
;         const unsigned gen = old / nloc;
;         if (old + 1u == (gen + 1u) * nloc) {
;             __builtin_amdgcn_fence(__ATOMIC_RELEASE, "agent");
;             asm volatile("s_waitcnt vmcnt(0)" ::: "memory");
;             const unsigned og = xb_add(&bar[XB_TOP], 1u);
;             const unsigned tg = og / nx;
;             if (og + 1u == (tg + 1u) * nx) xb_add(&bar[XB_TOPGEN], 1u);
;             else XB_SPIN(xb_ld(&bar[XB_TOPGEN]) == tg, bar);
;             __builtin_amdgcn_fence(__ATOMIC_ACQUIRE, "agent");
;             xb_add(&bar[XB_XGEN(b.x)], 1u);
;             asm volatile("s_waitcnt vmcnt(0)" ::: "memory");
;         } else {
;             XB_SPIN(xb_ld(&bar[XB_XGEN(b.x)]) == gen, bar);
;             __builtin_amdgcn_fence(__ATOMIC_ACQUIRE, "agent");
;             asm volatile("s_waitcnt vmcnt(0)" ::: "memory");
.LBB0_412:
	s_or_b64 exec, exec, s[8:9]
	v_cvt_f32_u32_e32 v7, v5
	s_waitcnt vmcnt(0)
	v_readfirstlane_b32 s6, v6
	v_sub_u32_e32 v6, 0, v5
	v_rcp_iflag_f32_e32 v7, v7
	v_add_u32_e32 v8, s6, v2
	v_mul_f32_e32 v7, 0x4f7ffffe, v7
	v_cvt_u32_f32_e32 v7, v7
	v_mul_lo_u32 v2, v6, v7
	v_mul_hi_u32 v2, v7, v2
	v_add_u32_e32 v2, v7, v2
	v_mul_hi_u32 v2, v8, v2
	v_mul_lo_u32 v6, v2, v5
	v_sub_u32_e32 v6, v8, v6
	v_add_u32_e32 v7, 1, v2
	v_cmp_ge_u32_e32 vcc, v6, v5
	s_nop 1
	v_cndmask_b32_e32 v2, v2, v7, vcc
	v_sub_u32_e32 v7, v6, v5
	v_cndmask_b32_e32 v6, v6, v7, vcc
	v_add_u32_e32 v7, 1, v2
	v_cmp_ge_u32_e32 vcc, v6, v5
	v_add_u32_e32 v6, 1, v8
	s_nop 0
	v_cndmask_b32_e32 v2, v2, v7, vcc
	v_mul_lo_u32 v7, v5, v2
	v_add_u32_e32 v5, v7, v5
	v_cmp_ne_u32_e32 vcc, v6, v5
	s_and_saveexec_b64 s[6:7], vcc
	s_xor_b64 s[6:7], exec, s[6:7]
	s_cbranch_execz .LBB0_426
	v_add_u32_e32 v19, 1, v6
	v_cmp_eq_u32_e32 vcc, v19, v5
	s_cbranch_vccz .Lxb_ew_1
	buffer_wbl2 sc1
.Lxb_ew_1:
	s_add_i32 s30, s40, 0x900
	s_lshl_b64 s[8:9], s[30:31], 2
	s_add_u32 s46, s34, s8
	s_addc_u32 s47, s35, s9
	s_waitcnt lgkmcnt(0)
	buffer_inv sc1
	global_load_dword v4, v3, s[46:47] sc1
	s_waitcnt vmcnt(0)
	v_cmp_eq_u32_e32 vcc, v4, v2
	s_and_saveexec_b64 s[8:9], vcc
	s_cbranch_execz .LBB0_425
	s_add_u32 s14, s4, 0x80200
	s_addc_u32 s15, s5, 0
	s_mov_b32 s30, 1
	s_mov_b64 s[52:53], 0
	s_branch .LBB0_416

; __device__ __forceinline__ unsigned xb_ld(unsigned* p)              { return __hip_atomic_load(p, __ATOMIC_RELAXED, __HIP_MEMORY_SCOPE_AGENT); }
; __device__ __forceinline__ unsigned xb_add(unsigned* p, unsigned v) { return __hip_atomic_fetch_add(p, v, __ATOMIC_RELAXED, __HIP_MEMORY_SCOPE_AGENT); }
; #define XB_SPIN(cond, bar) do { unsigned _sp = 0; while (cond) { __builtin_amdgcn_s_sleep(1); \
;     if ((++_sp & 255u) == 0u) { if (xb_ld(&(bar)[XB_TMO])) break; if (_sp > XB_SPIN_CAP) { atomicAdd(&(bar)[XB_TMO], 1u); break; } } } } while (0)
; __device__ __forceinline__ void xcd_barrier(const XcdBarrier& b) {
;     ...
;         const unsigned old = xb_add(&bar[XB_XSUB(b.x)], 1u);
;         const unsigned gen = old / nloc;
;         if (old + 1u == (gen + 1u) * nloc) {
;             __builtin_amdgcn_fence(__ATOMIC_RELEASE, "agent");
;             asm volatile("s_waitcnt vmcnt(0)" ::: "memory");
;             const unsigned og = xb_add(&bar[XB_TOP], 1u);
;             const unsigned tg = og / nx;
;             if (og + 1u == (tg + 1u) * nx) xb_add(&bar[XB_TOPGEN], 1u);
;             else XB_SPIN(xb_ld(&bar[XB_TOPGEN]) == tg, bar);
;             __builtin_amdgcn_fence(__ATOMIC_ACQUIRE, "agent");
;             xb_add(&bar[XB_XGEN(b.x)], 1u);
;             asm volatile("s_waitcnt vmcnt(0)" ::: "memory");
;         } else {
;             XB_SPIN(xb_ld(&bar[XB_XGEN(b.x)]) == gen, bar);
;             __builtin_amdgcn_fence(__ATOMIC_ACQUIRE, "agent");
;             asm volatile("s_waitcnt vmcnt(0)" ::: "memory");
.LBB0_654:
	s_or_b64 exec, exec, s[6:7]
	v_cvt_f32_u32_e32 v7, v5
	s_waitcnt vmcnt(0)
	v_readfirstlane_b32 s4, v6
	v_sub_u32_e32 v6, 0, v5
	v_rcp_iflag_f32_e32 v7, v7
	v_add_u32_e32 v8, s4, v2
	v_mul_f32_e32 v7, 0x4f7ffffe, v7
	v_cvt_u32_f32_e32 v7, v7
	v_mul_lo_u32 v2, v6, v7
	v_mul_hi_u32 v2, v7, v2
	v_add_u32_e32 v2, v7, v2
	v_mul_hi_u32 v2, v8, v2
	v_mul_lo_u32 v6, v2, v5
	v_sub_u32_e32 v6, v8, v6
	v_add_u32_e32 v7, 1, v2
	v_cmp_ge_u32_e32 vcc, v6, v5
	s_nop 1
	v_cndmask_b32_e32 v2, v2, v7, vcc
	v_sub_u32_e32 v7, v6, v5
	v_cndmask_b32_e32 v6, v6, v7, vcc
	v_add_u32_e32 v7, 1, v2
	v_cmp_ge_u32_e32 vcc, v6, v5
	v_add_u32_e32 v6, 1, v8
	s_nop 0
	v_cndmask_b32_e32 v2, v2, v7, vcc
	v_mul_lo_u32 v7, v5, v2
	v_add_u32_e32 v5, v7, v5
	v_cmp_ne_u32_e32 vcc, v6, v5
	s_and_saveexec_b64 s[4:5], vcc
	s_xor_b64 s[4:5], exec, s[4:5]
	s_cbranch_execz .LBB0_668
	v_add_u32_e32 v19, 1, v6
	v_cmp_eq_u32_e32 vcc, v19, v5
	s_cbranch_vccz .Lxb_ew_2
	buffer_wbl2 sc1
.Lxb_ew_2:
	s_add_i32 s30, s40, 0x900
	s_lshl_b64 s[6:7], s[30:31], 2
	s_add_u32 s14, s34, s6
	s_addc_u32 s15, s35, s7
	s_waitcnt lgkmcnt(0)
	buffer_inv sc1
	global_load_dword v4, v3, s[14:15] sc1
	s_waitcnt vmcnt(0)
	v_cmp_eq_u32_e32 vcc, v4, v2
	s_and_saveexec_b64 s[6:7], vcc
	s_cbranch_execz .LBB0_667
	s_add_u32 s8, s2, 0x80200
	s_addc_u32 s9, s3, 0
	s_mov_b32 s30, 1
	s_mov_b64 s[46:47], 0
	s_branch .LBB0_658

; __device__ __forceinline__ unsigned xb_ld(unsigned* p)              { return __hip_atomic_load(p, __ATOMIC_RELAXED, __HIP_MEMORY_SCOPE_AGENT); }
; #define XB_SPIN(cond, bar) do { unsigned _sp = 0; while (cond) { __builtin_amdgcn_s_sleep(1); \
;     if ((++_sp & 255u) == 0u) { if (xb_ld(&(bar)[XB_TMO])) break; if (_sp > XB_SPIN_CAP) { atomicAdd(&(bar)[XB_TMO], 1u); break; } } } } while (0)
; __device__ __forceinline__ void xcd_barrier(const XcdBarrier& b) {
;     ...
;         } else {
;             XB_SPIN(xb_ld(&bar[XB_XGEN(b.x)]) == gen, bar);
;             __builtin_amdgcn_fence(__ATOMIC_ACQUIRE, "agent");
;             asm volatile("s_waitcnt vmcnt(0)" ::: "memory");
.Lxb_ew_4:
	s_add_i32 s6, s40, 0x900
	s_mov_b32 s7, s31
	s_lshl_b64 s[6:7], s[6:7], 2
	s_add_u32 s14, s34, s6
	s_addc_u32 s15, s35, s7
	s_waitcnt lgkmcnt(0)
	buffer_inv sc1
	global_load_dword v4, v3, s[14:15] sc1
	s_waitcnt vmcnt(0)
	v_cmp_eq_u32_e32 vcc, v4, v2
	s_and_saveexec_b64 s[6:7], vcc
	s_cbranch_execz .LBB0_919
	s_add_u32 s8, s2, 0x80200
	s_addc_u32 s9, s3, 0
	s_mov_b32 s41, 1
	s_mov_b64 s[46:47], 0
	s_branch .LBB0_910

; __device__ __forceinline__ unsigned xb_ld(unsigned* p)              { return __hip_atomic_load(p, __ATOMIC_RELAXED, __HIP_MEMORY_SCOPE_AGENT); }
; #define XB_SPIN(cond, bar) do { unsigned _sp = 0; while (cond) { __builtin_amdgcn_s_sleep(1); \
;     if ((++_sp & 255u) == 0u) { if (xb_ld(&(bar)[XB_TMO])) break; if (_sp > XB_SPIN_CAP) { atomicAdd(&(bar)[XB_TMO], 1u); break; } } } } while (0)
; __device__ __forceinline__ void xcd_barrier(const XcdBarrier& b) {
;     ...
;         } else {
;             XB_SPIN(xb_ld(&bar[XB_XGEN(b.x)]) == gen, bar);
;             __builtin_amdgcn_fence(__ATOMIC_ACQUIRE, "agent");
;             asm volatile("s_waitcnt vmcnt(0)" ::: "memory");
.Lxb_ew_6:
	s_add_i32 s6, s40, 0x900
	s_mov_b32 s7, s31
	s_lshl_b64 s[6:7], s[6:7], 2
	s_add_u32 s46, s34, s6
	s_addc_u32 s47, s35, s7
	s_waitcnt lgkmcnt(0)
	buffer_inv sc1
	global_load_dword v4, v3, s[46:47] sc1
	s_waitcnt vmcnt(0)
	v_cmp_eq_u32_e32 vcc, v4, v2
	s_and_saveexec_b64 s[6:7], vcc
	s_cbranch_execz .LBB0_1112
	s_add_u32 s14, s2, 0x80200
	s_addc_u32 s15, s3, 0
	s_mov_b32 s41, 1
	s_mov_b64 s[52:53], 0
	s_branch .LBB0_1103

; __device__ __forceinline__ unsigned xb_ld(unsigned* p)              { return __hip_atomic_load(p, __ATOMIC_RELAXED, __HIP_MEMORY_SCOPE_AGENT); }
; __device__ __forceinline__ unsigned xb_add(unsigned* p, unsigned v) { return __hip_atomic_fetch_add(p, v, __ATOMIC_RELAXED, __HIP_MEMORY_SCOPE_AGENT); }
; #define XB_SPIN(cond, bar) do { unsigned _sp = 0; while (cond) { __builtin_amdgcn_s_sleep(1); \
;     if ((++_sp & 255u) == 0u) { if (xb_ld(&(bar)[XB_TMO])) break; if (_sp > XB_SPIN_CAP) { atomicAdd(&(bar)[XB_TMO], 1u); break; } } } } while (0)
; __device__ __forceinline__ void xcd_barrier(const XcdBarrier& b) {
;     ...
;         const unsigned old = xb_add(&bar[XB_XSUB(b.x)], 1u);
;         const unsigned gen = old / nloc;
;         if (old + 1u == (gen + 1u) * nloc) {
;             __builtin_amdgcn_fence(__ATOMIC_RELEASE, "agent");
;             asm volatile("s_waitcnt vmcnt(0)" ::: "memory");
;             const unsigned og = xb_add(&bar[XB_TOP], 1u);
;             const unsigned tg = og / nx;
;             if (og + 1u == (tg + 1u) * nx) xb_add(&bar[XB_TOPGEN], 1u);
;             else XB_SPIN(xb_ld(&bar[XB_TOPGEN]) == tg, bar);
;             __builtin_amdgcn_fence(__ATOMIC_ACQUIRE, "agent");
;             xb_add(&bar[XB_XGEN(b.x)], 1u);
;             asm volatile("s_waitcnt vmcnt(0)" ::: "memory");
;         } else {
;             XB_SPIN(xb_ld(&bar[XB_XGEN(b.x)]) == gen, bar);
;             __builtin_amdgcn_fence(__ATOMIC_ACQUIRE, "agent");
;             asm volatile("s_waitcnt vmcnt(0)" ::: "memory");
.LBB0_1167:
	s_or_b64 exec, exec, s[14:15]
	v_cvt_f32_u32_e32 v7, v5
	s_waitcnt vmcnt(0)
	v_readfirstlane_b32 s6, v6
	v_sub_u32_e32 v6, 0, v5
	v_rcp_iflag_f32_e32 v7, v7
	v_add_u32_e32 v8, s6, v2
	v_mul_f32_e32 v7, 0x4f7ffffe, v7
	v_cvt_u32_f32_e32 v7, v7
	v_mul_lo_u32 v2, v6, v7
	v_mul_hi_u32 v2, v7, v2
	v_add_u32_e32 v2, v7, v2
	v_mul_hi_u32 v2, v8, v2
	v_mul_lo_u32 v6, v2, v5
	v_sub_u32_e32 v6, v8, v6
	v_add_u32_e32 v7, 1, v2
	v_cmp_ge_u32_e32 vcc, v6, v5
	s_nop 1
	v_cndmask_b32_e32 v2, v2, v7, vcc
	v_sub_u32_e32 v7, v6, v5
	v_cndmask_b32_e32 v6, v6, v7, vcc
	v_add_u32_e32 v7, 1, v2
	v_cmp_ge_u32_e32 vcc, v6, v5
	v_add_u32_e32 v6, 1, v8
	s_nop 0
	v_cndmask_b32_e32 v2, v2, v7, vcc
	v_mul_lo_u32 v7, v5, v2
	v_add_u32_e32 v5, v7, v5
	v_cmp_ne_u32_e32 vcc, v6, v5
	s_and_saveexec_b64 s[6:7], vcc
	s_xor_b64 s[6:7], exec, s[6:7]
	s_cbranch_execz .LBB0_1181
	v_add_u32_e32 v19, 1, v6
	v_cmp_eq_u32_e32 vcc, v19, v5
	s_cbranch_vccz .Lxb_ew_7
	buffer_wbl2 sc1
.Lxb_ew_7:
	s_add_i32 s10, s40, 0x900
	s_mov_b32 s11, s31
	s_lshl_b64 s[10:11], s[10:11], 2
	s_add_u32 s52, s34, s10
	s_addc_u32 s53, s35, s11
	s_waitcnt lgkmcnt(0)
	buffer_inv sc1
	global_load_dword v4, v3, s[52:53] sc1
	s_waitcnt vmcnt(0)
	v_cmp_eq_u32_e32 vcc, v4, v2
	s_and_saveexec_b64 s[14:15], vcc
	s_cbranch_execz .LBB0_1180
	s_add_u32 s46, s4, 0x80200
	s_addc_u32 s47, s5, 0
	s_mov_b32 s41, 1
	s_mov_b64 s[58:59], 0
	s_branch .LBB0_1171

; __device__ __forceinline__ unsigned xb_ld(unsigned* p)              { return __hip_atomic_load(p, __ATOMIC_RELAXED, __HIP_MEMORY_SCOPE_AGENT); }
; #define XB_SPIN(cond, bar) do { unsigned _sp = 0; while (cond) { __builtin_amdgcn_s_sleep(1); \
;     if ((++_sp & 255u) == 0u) { if (xb_ld(&(bar)[XB_TMO])) break; if (_sp > XB_SPIN_CAP) { atomicAdd(&(bar)[XB_TMO], 1u); break; } } } } while (0)
; __device__ __forceinline__ void xcd_barrier(const XcdBarrier& b) {
;     ...
;         } else {
;             XB_SPIN(xb_ld(&bar[XB_XGEN(b.x)]) == gen, bar);
;             __builtin_amdgcn_fence(__ATOMIC_ACQUIRE, "agent");
;             asm volatile("s_waitcnt vmcnt(0)" ::: "memory");
.Lxb_ew_8:
	s_add_i32 s30, s40, 0x900
	s_lshl_b64 s[6:7], s[30:31], 2
	s_add_u32 s46, s34, s6
	s_addc_u32 s47, s35, s7
	s_waitcnt lgkmcnt(0)
	buffer_inv sc1
	global_load_dword v4, v3, s[46:47] sc1
	s_waitcnt vmcnt(0)
	v_cmp_eq_u32_e32 vcc, v4, v2
	s_and_saveexec_b64 s[6:7], vcc
	s_cbranch_execz .LBB0_1274
	s_add_u32 s14, s2, 0x80200
	s_addc_u32 s15, s3, 0
	s_mov_b32 s30, 1
	s_mov_b64 s[52:53], 0
	s_branch .LBB0_1265
